# KV-cache bf16 copy loop two iterations per trip (4 loads in flight); final RMS norm rows software-pipelined (next row prefetched, x2 unroll)
# speedup vs baseline: 1.0039x; 1.0039x over previous
.LBB0_1585:
	s_mov_b32 s2, 37
	v_readlane_b32 s3, v254, 4
	v_ashrrev_i32_e32 v0, 6, v179
	s_nop 0
	v_add_u32_e32 v16, s3, v0
	s_movk_i32 s3, 0x4000
	v_cmp_gt_i32_e32 vcc, s3, v16
	s_and_saveexec_b64 s[4:5], vcc
	v_readlane_b32 s8, v254, 55
	v_readlane_b32 s6, v254, 53
	v_readlane_b32 s9, v254, 56
	v_readlane_b32 s7, v254, 54
	s_cbranch_execz .LBB0_1588
	s_ashr_i32 s3, s2, 31
	s_lshl_b64 s[2:3], s[2:3], 3
	s_add_u32 s0, s0, s2
	s_addc_u32 s1, s1, s3
	s_load_dwordx2 s[0:1], s[0:1], 0x0
	v_lshlrev_b32_e32 v0, 4, v179
	v_and_b32_e32 v17, 0x3f0, v0
	s_mov_b64 s[2:3], 0
	s_mov_b32 s4, 0x800000
	s_waitcnt lgkmcnt(0)
	global_load_dwordx4 v[0:3], v17, s[0:1]
	global_load_dwordx4 v[4:7], v17, s[0:1] offset:1024
	global_load_dwordx4 v[8:11], v17, s[0:1] offset:2048
	global_load_dwordx4 v[12:15], v17, s[0:1] offset:3072
	v_ashrrev_i32_e32 v17, 31, v16
	v_lshlrev_b64 v[18:19], 12, v[16:17]
	v_and_b32_e32 v17, 63, v179
	v_lshl_or_b32 v18, v17, 4, v18
	v_lshl_add_u64 v[18:19], s[30:31], 0, v[18:19]
	s_mov_b64 s[0:1], 0xc00
	v_lshl_add_u64 v[18:19], v[18:19], 0, s[0:1]
	v_mov_b32_e32 v17, 0x358637bd
	s_movk_i32 s5, 0x3fff
	global_load_dwordx4 v[20:23], v[18:19], off offset:-3072
	global_load_dwordx4 v[24:27], v[18:19], off offset:-2048
	global_load_dwordx4 v[28:31], v[18:19], off offset:-1024
	global_load_dwordx4 v[32:35], v[18:19], off
.LBB0_1587:
	v_lshl_add_u64 v[60:61], v[18:19], 0, s[8:9]
	global_load_dwordx4 v[44:47], v[60:61], off offset:-3072
	global_load_dwordx4 v[48:51], v[60:61], off offset:-2048
	global_load_dwordx4 v[52:55], v[60:61], off offset:-1024
	global_load_dwordx4 v[56:59], v[60:61], off
	v_add_u32_e32 v16, s6, v16
	s_waitcnt vmcnt(4)
	v_mul_f32_e32 v36, v21, v21
	v_mul_f32_e32 v37, v23, v23
	v_mul_f32_e32 v38, v25, v25
	v_mul_f32_e32 v39, v27, v27
	v_mul_f32_e32 v40, v29, v29
	v_mul_f32_e32 v41, v31, v31
	v_fmac_f32_e32 v36, v20, v20
	v_fmac_f32_e32 v37, v22, v22
	v_fmac_f32_e32 v38, v24, v24
	v_fmac_f32_e32 v39, v26, v26
	v_mul_f32_e32 v42, v33, v33
	v_mul_f32_e32 v43, v35, v35
	v_fmac_f32_e32 v40, v28, v28
	v_fmac_f32_e32 v41, v30, v30
	v_add_f32_e32 v36, v36, v37
	v_add_f32_e32 v37, v38, v39
	v_fmac_f32_e32 v42, v32, v32
	v_fmac_f32_e32 v43, v34, v34
	v_add_f32_e32 v38, v40, v41
	v_add_f32_e32 v36, v36, v37
	v_add_f32_e32 v39, v42, v43
	v_add_f32_e32 v36, v36, v38
	v_add_f32_e32 v36, v36, v39
	s_nop 1
	v_add_f32_dpp v36, v36, v36 quad_perm:[1,0,3,2] row_mask:0xf bank_mask:0xf bound_ctrl:1
	s_nop 1
	v_add_f32_dpp v36, v36, v36 quad_perm:[2,3,0,1] row_mask:0xf bank_mask:0xf bound_ctrl:1
	s_nop 1
	v_add_f32_dpp v36, v36, v36 row_half_mirror row_mask:0xf bank_mask:0xf bound_ctrl:1
	s_nop 1
	v_add_f32_dpp v36, v36, v36 row_mirror row_mask:0xf bank_mask:0xf bound_ctrl:1
	v_mov_b32_e32 v37, v36
	s_nop 1
	v_permlane16_swap_b32_e32 v36, v37
	v_add_f32_e32 v36, v36, v37
	v_mov_b32_e32 v37, v36
	s_nop 1
	v_permlane32_swap_b32_e32 v36, v37
	v_add_f32_e32 v36, v36, v37
	v_fmamk_f32 v36, v36, 0x3a800000, v17
	v_mul_f32_e32 v37, 0x4b800000, v36
	v_cmp_gt_f32_e32 vcc, s4, v36
	s_nop 1
	v_cndmask_b32_e32 v36, v36, v37, vcc
	v_rsq_f32_e32 v36, v36
	s_nop 0
	v_mul_f32_e32 v37, 0x45800000, v36
	v_cndmask_b32_e32 v36, v36, v37, vcc
	v_pk_mul_f32 v[20:21], v[20:21], v[36:37] op_sel_hi:[1,0]
	v_pk_mul_f32 v[22:23], v[22:23], v[36:37] op_sel_hi:[1,0]
	v_pk_mul_f32 v[24:25], v[24:25], v[36:37] op_sel_hi:[1,0]
	v_pk_mul_f32 v[26:27], v[26:27], v[36:37] op_sel_hi:[1,0]
	v_pk_mul_f32 v[28:29], v[28:29], v[36:37] op_sel_hi:[1,0]
	v_pk_mul_f32 v[30:31], v[30:31], v[36:37] op_sel_hi:[1,0]
	v_pk_mul_f32 v[32:33], v[32:33], v[36:37] op_sel_hi:[1,0]
	v_pk_mul_f32 v[34:35], v[34:35], v[36:37] op_sel_hi:[1,0]
	v_pk_mul_f32 v[22:23], v[2:3], v[22:23]
	v_pk_mul_f32 v[20:21], v[0:1], v[20:21]
	v_pk_mul_f32 v[26:27], v[6:7], v[26:27]
	v_pk_mul_f32 v[24:25], v[4:5], v[24:25]
	v_pk_mul_f32 v[30:31], v[10:11], v[30:31]
	v_pk_mul_f32 v[28:29], v[8:9], v[28:29]
	v_pk_mul_f32 v[34:35], v[14:15], v[34:35]
	v_pk_mul_f32 v[32:33], v[12:13], v[32:33]
	global_store_dwordx4 v[18:19], v[20:23], off offset:-3072
	global_store_dwordx4 v[18:19], v[24:27], off offset:-2048
	global_store_dwordx4 v[18:19], v[28:31], off offset:-1024
	global_store_dwordx4 v[18:19], v[32:35], off
	v_lshl_add_u64 v[18:19], v[60:61], 0, s[8:9]
	global_load_dwordx4 v[20:23], v[18:19], off offset:-3072
	global_load_dwordx4 v[24:27], v[18:19], off offset:-2048
	global_load_dwordx4 v[28:31], v[18:19], off offset:-1024
	global_load_dwordx4 v[32:35], v[18:19], off
	v_add_u32_e32 v16, s6, v16
	v_cmp_lt_i32_e64 s[0:1], s5, v16
	s_or_b64 s[2:3], s[0:1], s[2:3]
	s_waitcnt vmcnt(8)
	v_mul_f32_e32 v36, v45, v45
	v_mul_f32_e32 v37, v47, v47
	v_mul_f32_e32 v38, v49, v49
	v_mul_f32_e32 v39, v51, v51
	v_mul_f32_e32 v40, v53, v53
	v_mul_f32_e32 v41, v55, v55
	v_fmac_f32_e32 v36, v44, v44
	v_fmac_f32_e32 v37, v46, v46
	v_fmac_f32_e32 v38, v48, v48
	v_fmac_f32_e32 v39, v50, v50
	v_mul_f32_e32 v42, v57, v57
	v_mul_f32_e32 v43, v59, v59
	v_fmac_f32_e32 v40, v52, v52
	v_fmac_f32_e32 v41, v54, v54
	v_add_f32_e32 v36, v36, v37
	v_add_f32_e32 v37, v38, v39
	v_fmac_f32_e32 v42, v56, v56
	v_fmac_f32_e32 v43, v58, v58
	v_add_f32_e32 v38, v40, v41
	v_add_f32_e32 v36, v36, v37
	v_add_f32_e32 v39, v42, v43
	v_add_f32_e32 v36, v36, v38
	v_add_f32_e32 v36, v36, v39
	s_nop 1
	v_add_f32_dpp v36, v36, v36 quad_perm:[1,0,3,2] row_mask:0xf bank_mask:0xf bound_ctrl:1
	s_nop 1
	v_add_f32_dpp v36, v36, v36 quad_perm:[2,3,0,1] row_mask:0xf bank_mask:0xf bound_ctrl:1
	s_nop 1
	v_add_f32_dpp v36, v36, v36 row_half_mirror row_mask:0xf bank_mask:0xf bound_ctrl:1
	s_nop 1
	v_add_f32_dpp v36, v36, v36 row_mirror row_mask:0xf bank_mask:0xf bound_ctrl:1
	v_mov_b32_e32 v37, v36
	s_nop 1
	v_permlane16_swap_b32_e32 v36, v37
	v_add_f32_e32 v36, v36, v37
	v_mov_b32_e32 v37, v36
	s_nop 1
	v_permlane32_swap_b32_e32 v36, v37
	v_add_f32_e32 v36, v36, v37
	v_fmamk_f32 v36, v36, 0x3a800000, v17
	v_mul_f32_e32 v37, 0x4b800000, v36
	v_cmp_gt_f32_e32 vcc, s4, v36
	s_nop 1
	v_cndmask_b32_e32 v36, v36, v37, vcc
	v_rsq_f32_e32 v36, v36
	s_nop 0
	v_mul_f32_e32 v37, 0x45800000, v36
	v_cndmask_b32_e32 v36, v36, v37, vcc
	v_pk_mul_f32 v[44:45], v[44:45], v[36:37] op_sel_hi:[1,0]
	v_pk_mul_f32 v[46:47], v[46:47], v[36:37] op_sel_hi:[1,0]
	v_pk_mul_f32 v[48:49], v[48:49], v[36:37] op_sel_hi:[1,0]
	v_pk_mul_f32 v[50:51], v[50:51], v[36:37] op_sel_hi:[1,0]
	v_pk_mul_f32 v[52:53], v[52:53], v[36:37] op_sel_hi:[1,0]
	v_pk_mul_f32 v[54:55], v[54:55], v[36:37] op_sel_hi:[1,0]
	v_pk_mul_f32 v[56:57], v[56:57], v[36:37] op_sel_hi:[1,0]
	v_pk_mul_f32 v[58:59], v[58:59], v[36:37] op_sel_hi:[1,0]
	v_pk_mul_f32 v[46:47], v[2:3], v[46:47]
	v_pk_mul_f32 v[44:45], v[0:1], v[44:45]
	v_pk_mul_f32 v[50:51], v[6:7], v[50:51]
	v_pk_mul_f32 v[48:49], v[4:5], v[48:49]
	v_pk_mul_f32 v[54:55], v[10:11], v[54:55]
	v_pk_mul_f32 v[52:53], v[8:9], v[52:53]
	v_pk_mul_f32 v[58:59], v[14:15], v[58:59]
	v_pk_mul_f32 v[56:57], v[12:13], v[56:57]
	global_store_dwordx4 v[60:61], v[44:47], off offset:-3072
	global_store_dwordx4 v[60:61], v[48:51], off offset:-2048
	global_store_dwordx4 v[60:61], v[52:55], off offset:-1024
	global_store_dwordx4 v[60:61], v[56:59], off
	s_andn2_b64 exec, exec, s[2:3]
	s_cbranch_execnz .LBB0_1587
